# v95 + prep_run rows: pooling lines of the row two steps ahead touched at the row latch (dummy destinations), loop-top vmcnt(0) moved to the preamble
# baseline (speedup 1.0000x reference)
.LBB0_447:
	s_and_b64 vcc, exec, s[0:1]
	s_cbranch_vccz .LBB0_557
	s_movk_i32 s0, 0xff
	v_cmp_lt_i32_e32 vcc, s0, v81
	s_and_saveexec_b64 s[0:1], vcc
	s_xor_b64 s[42:43], exec, s[0:1]
	s_cbranch_execz .LBB0_531
	s_movk_i32 s0, 0x33f
	v_cmp_lt_u32_e32 vcc, s0, v81
	s_and_saveexec_b64 s[0:1], vcc
	s_xor_b64 s[16:17], exec, s[0:1]
	s_cbranch_execz .LBB0_501
	s_movk_i32 s0, 0x6bf
	v_cmp_lt_u32_e32 vcc, s0, v81
	v_readlane_b32 s4, v254, 28
	v_readlane_b32 s0, v255, 7
	v_readlane_b32 s5, v254, 29
	s_add_u32 s2, s4, 0x16f00000
	v_readlane_b32 s1, v255, 8
	s_addc_u32 s3, s5, 0
	s_lshl_b64 s[0:1], s[0:1], 2
	s_add_u32 s0, s4, s0
	s_addc_u32 s1, s5, s1
	s_add_u32 s18, s0, 0x2000
	s_addc_u32 s19, s1, 0
	s_and_saveexec_b64 s[0:1], vcc
	s_xor_b64 s[28:29], exec, s[0:1]
	s_cbranch_execz .LBB0_475
	v_mov_b32_e32 v0, 0xfffff800
	v_mov_b32_e32 v1, -1
	v_mad_u64_u32 v[8:9], s[0:1], v81, 10, v[0:1]
	v_mov_b32_e32 v9, v236
	v_readlane_b32 s4, v255, 11
	v_and_b32_e32 v17, 15, v9
	v_bfe_u32 v19, v9, 4, 2
	v_lshlrev_b32_e32 v21, 2, v17
	v_lshlrev_b32_e32 v12, 6, v19
	v_or_b32_e32 v23, 8, v19
	v_readlane_b32 s5, v255, 12
	v_or_b32_e32 v20, 0x100, v21
	v_min_u32_e32 v0, 9, v23
	v_mov_b64_e32 v[10:11], s[4:5]
	s_movk_i32 s0, 0x1200
	v_or_b32_e32 v22, v12, v21
	v_or_b32_e32 v16, v12, v20
	v_lshlrev_b32_e32 v25, 6, v0
	v_mad_i64_i32 v[10:11], s[0:1], v8, s0, v[10:11]
	v_lshlrev_b32_e32 v160, 1, v22
	v_lshl_add_u64 v[12:13], v[10:11], 0, v[160:161]
	v_lshlrev_b32_e32 v160, 1, v16
	v_or_b32_e32 v24, v25, v21
	v_lshlrev_b32_e32 v4, 4, v17
	v_lshl_add_u64 v[14:15], v[10:11], 0, v[160:161]
	v_lshlrev_b32_e32 v160, 1, v24
	global_load_dwordx4 v[0:3], v4, s[18:19]
	s_nop 0
	global_load_dwordx4 v[4:7], v4, s[18:19] offset:1024
	v_lshl_add_u64 v[10:11], v[10:11], 0, v[160:161]
	global_load_dwordx2 v[46:47], v[12:13], off offset:512
	global_load_dwordx2 v[44:45], v[14:15], off offset:512
	global_load_dwordx2 v[38:39], v[10:11], off offset:512
	v_and_b32_e32 v10, 63, v9
	v_and_b32_e32 v9, 4, v9
	v_cmp_eq_u32_e64 s[36:37], 0, v9
	v_and_b32_e32 v9, 12, v21
	v_cvt_f32_ubyte0_e32 v14, v9
	v_mul_f32_e32 v14, 0xbf549a78, v14
	v_exp_f32_e32 v59, v14
	v_or_b32_e32 v14, 1, v9
	v_cvt_f32_ubyte0_e32 v14, v14
	v_mul_f32_e32 v14, 0xbf549a78, v14
	v_exp_f32_e32 v60, v14
	v_or_b32_e32 v14, 2, v9
	v_or_b32_e32 v9, 3, v9
	v_cvt_f32_ubyte0_e32 v14, v14
	v_cvt_f32_ubyte0_e32 v9, v9
	v_mul_f32_e32 v14, 0xbf549a78, v14
	v_mul_f32_e32 v9, 0xbf549a78, v9
	v_exp_f32_e32 v61, v14
	v_exp_f32_e32 v62, v9
	v_readlane_b32 s0, v254, 28
	v_add_u32_e32 v18, 0x100, v16
	v_or_b32_e32 v20, v25, v20
	v_mov_b32_e32 v64, 0
	v_lshlrev_b32_e32 v160, 3, v10
	v_readlane_b32 s1, v254, 29
	v_cmp_gt_u32_e32 vcc, 10, v23
	v_lshlrev_b32_e64 v58, v19, 1
	v_lshl_add_u64 v[10:11], s[4:5], 0, v[160:161]
	v_cmp_gt_u32_e64 s[38:39], 8, v17
	v_lshl_add_u64 v[12:13], s[2:3], 0, v[160:161]
	v_lshl_add_u64 v[14:15], s[0:1], 0, v[160:161]
	s_mov_b32 s14, 0
	v_lshlrev_b32_e32 v16, 1, v16
	v_lshlrev_b32_e32 v18, 1, v18
	v_lshlrev_b32_e32 v20, 1, v20
	v_lshlrev_b32_e32 v22, 1, v22
	v_lshlrev_b32_e32 v24, 1, v24
	v_mov_b32_e32 v63, v8
	v_mov_b32_e32 v23, 0
	v_mov_b32_e32 v40, 0
	v_mov_b32_e32 v41, v64
	v_mov_b32_e32 v42, 0
	v_mov_b32_e32 v43, v64
	s_waitcnt vmcnt(0)
	s_branch .LBB0_453
.LBB0_452:
	s_or_b64 exec, exec, s[0:1]
	v_sub_u32_e32 v9, v19, v64
	v_cvt_f32_i32_e32 v9, v9
	s_waitcnt vmcnt(2)
	v_lshlrev_b32_e32 v200, 16, v196
	v_and_b32_e32 v201, 0xffff0000, v196
	v_lshlrev_b32_e32 v202, 16, v198
	v_and_b32_e32 v203, 0xffff0000, v198
	v_pk_add_f32 v[200:201], v[200:201], v[202:203] neg_lo:[0,1] neg_hi:[0,1]
	v_lshlrev_b32_e32 v198, 16, v199
	v_pk_add_f32 v[42:43], v[42:43], v[200:201]
	v_lshlrev_b32_e32 v200, 16, v197
	v_and_b32_e32 v201, 0xffff0000, v197
	v_and_b32_e32 v199, 0xffff0000, v199
	v_pk_add_f32 v[200:201], v[200:201], v[198:199] neg_lo:[0,1] neg_hi:[0,1]
	s_nop 0
	v_pk_add_f32 v[40:41], v[40:41], v[200:201]
	v_bfe_u32 v222, v236, 4, 2
	v_lshlrev_b32_e64 v222, v222, 1
	v_add_u32_e32 v222, -1, v222
	v_mul_u32_u24_e32 v208, 0x1200, v222
	v_mov_b32_e32 v209, 0
	v_lshl_add_u64 v[212:213], v[206:207], 0, v[208:209]
	s_nop 1
	global_load_dwordx2 v[216:217], v[206:207], off
	global_load_dwordx2 v[218:219], v[212:213], off
	v_lshlrev_b32_e32 v38, 16, v36
	v_and_b32_e32 v39, 0xffff0000, v36
	s_add_i32 s14, s14, 1
	v_rcp_iflag_f32_e32 v34, v9
	v_lshlrev_b64 v[26:27], 11, v[26:27]
	v_lshl_add_u64 v[26:27], v[12:13], 0, v[26:27]
	v_add_u32_e32 v63, 1, v63
	v_pk_fma_f32 v[38:39], v[34:35], v[42:43], v[38:39] op_sel_hi:[0,1,1] neg_lo:[0,0,1] neg_hi:[0,0,1]
	v_cvt_pk_bf16_f32 v36, v38, v39
	v_lshlrev_b32_e32 v38, 16, v37
	v_and_b32_e32 v39, 0xffff0000, v37
	v_pk_fma_f32 v[34:35], v[34:35], v[40:41], v[38:39] op_sel_hi:[0,1,1] neg_lo:[0,0,1] neg_hi:[0,0,1]
	v_cvt_pk_bf16_f32 v37, v34, v35
	s_cmp_eq_u32 s14, 10
	v_mov_b32_e32 v23, v19
	v_mov_b32_e32 v46, v28
	v_mov_b32_e32 v47, v29
	v_mov_b32_e32 v44, v30
	v_mov_b32_e32 v45, v31
	v_mov_b32_e32 v38, v32
	v_mov_b32_e32 v39, v33
	global_store_dwordx2 v[26:27], v[36:37], off
	s_cbranch_scc1 .LBB0_475

.LBB0_455:
	s_movk_i32 s0, 0x3fff
	v_cmp_lt_i32_e64 s[40:41], s0, v26
	v_mov_b32_e32 v9, 0x7ff
	s_movk_i32 s0, 0x1200
	v_cndmask_b32_e64 v9, v9, v238, s[40:41]
	v_and_b32_e32 v9, v9, v26
	v_sub_u32_e32 v17, v26, v9
	v_mad_i64_i32 v[48:49], s[0:1], v17, s0, v[10:11]
	v_mul_u32_u24_e32 v17, 0x900, v9
	v_lshlrev_b32_e32 v160, 1, v17
	v_lshl_add_u64 v[36:37], v[48:49], 0, v[160:161]
	s_movk_i32 s98, 0x2400
	s_mov_b32 s99, 0
	v_lshl_add_u64 v[206:207], v[36:37], 0, s[98:99]
	global_load_dwordx2 v[36:37], v[36:37], off
	v_mov_b32_e32 v17, 0x800
	s_cmp_lg_u32 s14, 0
	v_cndmask_b32_e64 v19, v17, v245, s[40:41]
	v_add_u32_e32 v21, v9, v58
	s_cselect_b64 s[4:5], -1, 0
	v_cmp_ne_u32_e64 s[0:1], 0, v9
	v_ashrrev_i32_e32 v27, 31, v26
	v_sub_u32_e32 v17, v9, v58
	v_min_u32_e32 v19, v21, v19
	s_and_b64 s[0:1], s[4:5], s[0:1]
	v_mov_b32_e32 v196, 0
	v_mov_b32_e32 v197, 0
	v_mov_b32_e32 v198, 0
	v_mov_b32_e32 v199, 0
	s_and_saveexec_b64 s[4:5], s[0:1]
	s_xor_b64 s[4:5], exec, s[4:5]
	s_cbranch_execz .LBB0_461
	v_cmp_gt_u32_e64 s[0:1], v19, v23
	v_mov_b32_e32 v198, 0
	v_mov_b32_e32 v196, 0
	v_mov_b32_e32 v197, 0
	s_and_saveexec_b64 s[6:7], s[0:1]
	s_cbranch_execz .LBB0_458
	v_add_u32_e32 v21, -1, v19
	s_movk_i32 s0, 0x1200
	v_mad_u64_u32 v[52:53], s[0:1], v21, s0, v[48:49]
	global_load_dwordx2 v[196:197], v[52:53], off

.LBB0_475:
	s_andn2_saveexec_b64 s[28:29], s[28:29]
	s_cbranch_execz .LBB0_500
	v_mov_b32_e32 v0, 0xfffff140
	v_mov_b32_e32 v1, -1
	v_mad_u64_u32 v[8:9], s[0:1], v81, 11, v[0:1]
	v_mov_b32_e32 v9, v236
	v_readlane_b32 s4, v255, 11
	v_and_b32_e32 v17, 15, v9
	v_bfe_u32 v19, v9, 4, 2
	v_lshlrev_b32_e32 v21, 2, v17
	v_lshlrev_b32_e32 v12, 6, v19
	v_or_b32_e32 v23, 8, v19
	v_readlane_b32 s5, v255, 12
	v_or_b32_e32 v20, 0x100, v21
	v_min_u32_e32 v0, 9, v23
	v_mov_b64_e32 v[10:11], s[4:5]
	s_movk_i32 s0, 0x1200
	v_or_b32_e32 v22, v12, v21
	v_or_b32_e32 v16, v12, v20
	v_lshlrev_b32_e32 v25, 6, v0
	v_mad_u64_u32 v[10:11], s[0:1], v8, s0, v[10:11]
	v_lshlrev_b32_e32 v160, 1, v22
	v_lshl_add_u64 v[12:13], v[10:11], 0, v[160:161]
	v_lshlrev_b32_e32 v160, 1, v16
	v_or_b32_e32 v24, v25, v21
	v_lshlrev_b32_e32 v4, 4, v17
	v_lshl_add_u64 v[14:15], v[10:11], 0, v[160:161]
	v_lshlrev_b32_e32 v160, 1, v24
	global_load_dwordx4 v[0:3], v4, s[18:19]
	s_nop 0
	global_load_dwordx4 v[4:7], v4, s[18:19] offset:1024
	v_lshl_add_u64 v[10:11], v[10:11], 0, v[160:161]
	global_load_dwordx2 v[46:47], v[12:13], off offset:512
	global_load_dwordx2 v[44:45], v[14:15], off offset:512
	global_load_dwordx2 v[38:39], v[10:11], off offset:512
	v_and_b32_e32 v10, 63, v9
	v_and_b32_e32 v9, 4, v9
	v_cmp_eq_u32_e64 s[36:37], 0, v9
	v_and_b32_e32 v9, 12, v21
	v_cvt_f32_ubyte0_e32 v14, v9
	v_mul_f32_e32 v14, 0xbf549a78, v14
	v_exp_f32_e32 v59, v14
	v_or_b32_e32 v14, 1, v9
	v_cvt_f32_ubyte0_e32 v14, v14
	v_mul_f32_e32 v14, 0xbf549a78, v14
	v_exp_f32_e32 v60, v14
	v_or_b32_e32 v14, 2, v9
	v_or_b32_e32 v9, 3, v9
	v_cvt_f32_ubyte0_e32 v14, v14
	v_cvt_f32_ubyte0_e32 v9, v9
	v_mul_f32_e32 v14, 0xbf549a78, v14
	v_mul_f32_e32 v9, 0xbf549a78, v9
	v_exp_f32_e32 v61, v14
	v_exp_f32_e32 v62, v9
	v_readlane_b32 s0, v254, 28
	v_add_u32_e32 v18, 0x100, v16
	v_or_b32_e32 v20, v25, v20
	v_mov_b32_e32 v64, 0
	v_lshlrev_b32_e32 v160, 3, v10
	v_readlane_b32 s1, v254, 29
	v_cmp_gt_u32_e32 vcc, 10, v23
	v_lshlrev_b32_e64 v58, v19, 1
	v_lshl_add_u64 v[10:11], s[4:5], 0, v[160:161]
	v_cmp_gt_u32_e64 s[38:39], 8, v17
	v_lshl_add_u64 v[12:13], s[2:3], 0, v[160:161]
	v_lshl_add_u64 v[14:15], s[0:1], 0, v[160:161]
	s_mov_b32 s10, 0
	v_lshlrev_b32_e32 v16, 1, v16
	v_lshlrev_b32_e32 v18, 1, v18
	v_lshlrev_b32_e32 v20, 1, v20
	v_lshlrev_b32_e32 v22, 1, v22
	v_lshlrev_b32_e32 v24, 1, v24
	v_mov_b32_e32 v63, v8
	v_mov_b32_e32 v23, 0
	v_mov_b32_e32 v40, 0
	v_mov_b32_e32 v41, v64
	v_mov_b32_e32 v42, 0
	v_mov_b32_e32 v43, v64
	s_waitcnt vmcnt(0)
	s_branch .LBB0_478
.LBB0_477:
	s_or_b64 exec, exec, s[0:1]
	v_sub_u32_e32 v9, v19, v64
	v_cvt_f32_i32_e32 v9, v9
	s_waitcnt vmcnt(2)
	v_lshlrev_b32_e32 v200, 16, v196
	v_and_b32_e32 v201, 0xffff0000, v196
	v_lshlrev_b32_e32 v202, 16, v198
	v_and_b32_e32 v203, 0xffff0000, v198
	v_pk_add_f32 v[200:201], v[200:201], v[202:203] neg_lo:[0,1] neg_hi:[0,1]
	v_lshlrev_b32_e32 v198, 16, v199
	v_pk_add_f32 v[42:43], v[42:43], v[200:201]
	v_lshlrev_b32_e32 v200, 16, v197
	v_and_b32_e32 v201, 0xffff0000, v197
	v_and_b32_e32 v199, 0xffff0000, v199
	v_pk_add_f32 v[200:201], v[200:201], v[198:199] neg_lo:[0,1] neg_hi:[0,1]
	s_nop 0
	v_pk_add_f32 v[40:41], v[40:41], v[200:201]
	v_bfe_u32 v222, v236, 4, 2
	v_lshlrev_b32_e64 v222, v222, 1
	v_add_u32_e32 v222, -1, v222
	v_mul_u32_u24_e32 v208, 0x1200, v222
	v_mov_b32_e32 v209, 0
	v_lshl_add_u64 v[212:213], v[206:207], 0, v[208:209]
	s_nop 1
	global_load_dwordx2 v[216:217], v[206:207], off
	global_load_dwordx2 v[218:219], v[212:213], off
	v_lshlrev_b32_e32 v38, 16, v36
	v_and_b32_e32 v39, 0xffff0000, v36
	s_add_i32 s10, s10, 1
	v_rcp_iflag_f32_e32 v34, v9
	v_lshlrev_b64 v[26:27], 11, v[26:27]
	v_lshl_add_u64 v[26:27], v[12:13], 0, v[26:27]
	v_add_u32_e32 v63, 1, v63
	v_pk_fma_f32 v[38:39], v[34:35], v[42:43], v[38:39] op_sel_hi:[0,1,1] neg_lo:[0,0,1] neg_hi:[0,0,1]
	v_cvt_pk_bf16_f32 v36, v38, v39
	v_lshlrev_b32_e32 v38, 16, v37
	v_and_b32_e32 v39, 0xffff0000, v37
	v_pk_fma_f32 v[34:35], v[34:35], v[40:41], v[38:39] op_sel_hi:[0,1,1] neg_lo:[0,0,1] neg_hi:[0,0,1]
	v_cvt_pk_bf16_f32 v37, v34, v35
	s_cmp_eq_u32 s10, 11
	v_mov_b32_e32 v23, v19
	v_mov_b32_e32 v46, v28
	v_mov_b32_e32 v47, v29
	v_mov_b32_e32 v44, v30
	v_mov_b32_e32 v45, v31
	v_mov_b32_e32 v38, v32
	v_mov_b32_e32 v39, v33
	global_store_dwordx2 v[26:27], v[36:37], off
	s_cbranch_scc1 .LBB0_500

.LBB0_480:
	s_movk_i32 s0, 0x3fff
	v_cmp_lt_i32_e64 s[40:41], s0, v26
	v_mov_b32_e32 v9, 0x7ff
	s_movk_i32 s0, 0x1200
	v_cndmask_b32_e64 v9, v9, v238, s[40:41]
	v_and_b32_e32 v9, v9, v26
	v_sub_u32_e32 v17, v26, v9
	v_mad_i64_i32 v[48:49], s[0:1], v17, s0, v[10:11]
	v_mul_u32_u24_e32 v17, 0x900, v9
	v_lshlrev_b32_e32 v160, 1, v17
	v_lshl_add_u64 v[36:37], v[48:49], 0, v[160:161]
	s_movk_i32 s98, 0x2400
	s_mov_b32 s99, 0
	v_lshl_add_u64 v[206:207], v[36:37], 0, s[98:99]
	global_load_dwordx2 v[36:37], v[36:37], off
	v_mov_b32_e32 v17, 0x800
	s_cmp_lg_u32 s10, 0
	v_cndmask_b32_e64 v19, v17, v245, s[40:41]
	v_add_u32_e32 v21, v9, v58
	s_cselect_b64 s[2:3], -1, 0
	v_cmp_ne_u32_e64 s[0:1], 0, v9
	v_ashrrev_i32_e32 v27, 31, v26
	v_sub_u32_e32 v17, v9, v58
	v_min_u32_e32 v19, v21, v19
	s_and_b64 s[0:1], s[2:3], s[0:1]
	v_mov_b32_e32 v196, 0
	v_mov_b32_e32 v197, 0
	v_mov_b32_e32 v198, 0
	v_mov_b32_e32 v199, 0
	s_and_saveexec_b64 s[2:3], s[0:1]
	s_xor_b64 s[2:3], exec, s[2:3]
	s_cbranch_execz .LBB0_486
	v_cmp_gt_u32_e64 s[0:1], v19, v23
	v_mov_b32_e32 v198, 0
	v_mov_b32_e32 v196, 0
	v_mov_b32_e32 v197, 0
	s_and_saveexec_b64 s[4:5], s[0:1]
	s_cbranch_execz .LBB0_483
	v_add_u32_e32 v21, -1, v19
	s_movk_i32 s0, 0x1200
	v_mad_u64_u32 v[52:53], s[0:1], v21, s0, v[48:49]
	global_load_dwordx2 v[196:197], v[52:53], off

.LBB0_501:
	s_andn2_saveexec_b64 s[2:3], s[16:17]
	s_cbranch_execz .LBB0_530
	v_add_u32_e32 v4, 0xffffff00, v81
	s_mov_b32 s0, 0xe38f
	v_mul_u32_u24_sdwa v1, v4, s0 dst_sel:DWORD dst_unused:UNUSED_PAD src0_sel:WORD_0 src1_sel:DWORD
	v_lshrrev_b32_e32 v2, 21, v1
	v_mul_lo_u16_e32 v3, 36, v2
	v_sub_u16_e32 v3, v4, v3
	v_mov_b32_e32 v0, v236
	v_lshrrev_b32_e32 v5, 22, v1
	v_cmp_lt_u16_e32 vcc, 31, v3
	v_lshlrev_b16_e32 v3, 6, v3
	s_and_saveexec_b64 s[0:1], vcc
	s_xor_b64 s[0:1], exec, s[0:1]
	v_lshlrev_b32_e32 v1, 8, v5
	s_movk_i32 s4, 0x3800
	v_add3_u32 v1, v3, v1, s4
	s_andn2_saveexec_b64 s[0:1], s[0:1]
	v_lshl_or_b32 v1, v5, 11, v3
	s_or_b64 exec, exec, s[0:1]
	v_readlane_b32 s8, v254, 28
	v_readlane_b32 s9, v254, 29
	s_movk_i32 s6, 0x1200
	v_lshlrev_b32_e32 v8, 7, v2
	v_mov_b64_e32 v[6:7], s[8:9]
	v_and_b32_e32 v5, 63, v0
	v_mad_u64_u32 v[0:1], s[0:1], v1, s6, v[6:7]
	v_and_b32_e32 v160, 0x80, v8
	v_lshl_add_u64 v[0:1], v[0:1], 0, v[160:161]
	v_lshlrev_b32_e32 v160, 1, v5
	v_lshl_add_u64 v[0:1], v[0:1], 0, v[160:161]
	s_mov_b32 s0, 0xb200000
	v_add_co_u32_e32 v8, vcc, s0, v0
	s_mov_b32 s0, 0xb201000
	s_nop 0
	v_addc_co_u32_e32 v9, vcc, 0, v1, vcc
	v_add_co_u32_e32 v10, vcc, s0, v0
	s_mov_b32 s0, 0xb202000
	s_nop 0
	v_addc_co_u32_e32 v11, vcc, 0, v1, vcc
	v_add_co_u32_e32 v12, vcc, s0, v0
	s_mov_b32 s0, 0xb203000
	s_nop 0
	v_addc_co_u32_e32 v13, vcc, 0, v1, vcc
	v_add_co_u32_e32 v14, vcc, s0, v0
	s_mov_b32 s0, 0xb204000
	s_nop 0
	v_addc_co_u32_e32 v15, vcc, 0, v1, vcc
	v_add_co_u32_e32 v16, vcc, s0, v0
	s_mov_b32 s0, 0xb206000
	s_nop 0
	v_addc_co_u32_e32 v17, vcc, 0, v1, vcc
	v_add_co_u32_e32 v18, vcc, s0, v0
	s_mov_b32 s0, 0xb207000
	s_nop 0
	v_addc_co_u32_e32 v19, vcc, 0, v1, vcc
	v_add_co_u32_e32 v20, vcc, s0, v0
	s_mov_b32 s0, 0xb208000
	s_nop 0
	v_addc_co_u32_e32 v21, vcc, 0, v1, vcc
	v_add_co_u32_e32 v22, vcc, s0, v0
	v_lshl_or_b32 v2, v2, 6, v5
	s_nop 0
	v_addc_co_u32_e32 v23, vcc, 0, v1, vcc
	global_load_ushort v8, v[8:9], off offset:1792
	s_nop 0
	global_load_ushort v9, v[10:11], off offset:2304
	global_load_ushort v24, v[12:13], off offset:2816
	global_load_ushort v25, v[14:15], off offset:3328
	global_load_ushort v26, v[16:17], off offset:3840
	global_load_ushort v27, v[18:19], off offset:256
	global_load_ushort v28, v[20:21], off offset:768
	global_load_ushort v29, v[22:23], off offset:1280
	s_mov_b32 s98, 0xb209700
	s_mov_b32 s99, 0
	v_lshl_add_u64 v[250:251], v[0:1], 0, s[98:99]
	s_movk_i32 s98, 0x1200
	s_nop 0
	global_load_ushort v196, v[250:251], off
	v_lshl_add_u64 v[250:251], v[250:251], 0, s[98:99]
	s_nop 0
	global_load_ushort v197, v[250:251], off
	v_lshl_add_u64 v[250:251], v[250:251], 0, s[98:99]
	s_nop 0
	global_load_ushort v198, v[250:251], off
	v_lshl_add_u64 v[250:251], v[250:251], 0, s[98:99]
	s_nop 0
	global_load_ushort v199, v[250:251], off
	v_lshl_add_u64 v[250:251], v[250:251], 0, s[98:99]
	s_nop 0
	global_load_ushort v200, v[250:251], off
	v_lshl_add_u64 v[250:251], v[250:251], 0, s[98:99]
	s_nop 0
	global_load_ushort v201, v[250:251], off
	v_lshl_add_u64 v[250:251], v[250:251], 0, s[98:99]
	s_nop 0
	global_load_ushort v202, v[250:251], off
	v_lshl_add_u64 v[250:251], v[250:251], 0, s[98:99]
	s_nop 0
	global_load_ushort v203, v[250:251], off
	v_lshl_add_u64 v[250:251], v[250:251], 0, s[98:99]
	s_nop 0
	global_load_ushort v206, v[250:251], off
	v_lshl_add_u64 v[250:251], v[250:251], 0, s[98:99]
	s_nop 0
	global_load_ushort v207, v[250:251], off
	v_lshl_add_u64 v[250:251], v[250:251], 0, s[98:99]
	s_nop 0
	global_load_ushort v208, v[250:251], off
	v_lshl_add_u64 v[250:251], v[250:251], 0, s[98:99]
	s_nop 0
	global_load_ushort v209, v[250:251], off
	v_lshl_add_u64 v[250:251], v[250:251], 0, s[98:99]
	s_nop 0
	global_load_ushort v210, v[250:251], off
	v_lshl_add_u64 v[250:251], v[250:251], 0, s[98:99]
	s_nop 0
	global_load_ushort v211, v[250:251], off
	v_lshl_add_u64 v[250:251], v[250:251], 0, s[98:99]
	s_nop 0
	global_load_ushort v212, v[250:251], off
	v_lshl_add_u64 v[250:251], v[250:251], 0, s[98:99]
	s_nop 0
	global_load_ushort v213, v[250:251], off
	v_lshl_add_u64 v[250:251], v[250:251], 0, s[98:99]
	s_nop 0
	global_load_ushort v214, v[250:251], off
	v_lshl_add_u64 v[250:251], v[250:251], 0, s[98:99]
	s_nop 0
	global_load_ushort v215, v[250:251], off
	v_lshl_add_u64 v[250:251], v[250:251], 0, s[98:99]
	s_nop 0
	global_load_ushort v216, v[250:251], off
	v_lshl_add_u64 v[250:251], v[250:251], 0, s[98:99]
	s_nop 0
	global_load_ushort v217, v[250:251], off
	v_lshl_add_u64 v[250:251], v[250:251], 0, s[98:99]
	s_nop 0
	global_load_ushort v218, v[250:251], off
	v_lshl_add_u64 v[250:251], v[250:251], 0, s[98:99]
	s_nop 0
	global_load_ushort v219, v[250:251], off
	v_lshl_add_u64 v[250:251], v[250:251], 0, s[98:99]
	s_nop 0
	global_load_ushort v220, v[250:251], off
	v_lshl_add_u64 v[250:251], v[250:251], 0, s[98:99]
	s_nop 0
	global_load_ushort v221, v[250:251], off
	v_lshl_add_u64 v[250:251], v[250:251], 0, s[98:99]
	s_nop 0
	global_load_ushort v222, v[250:251], off
	v_lshl_add_u64 v[250:251], v[250:251], 0, s[98:99]
	s_nop 0
	global_load_ushort v223, v[250:251], off
	v_lshl_add_u64 v[250:251], v[250:251], 0, s[98:99]
	s_nop 0
	global_load_ushort v224, v[250:251], off
	v_lshl_add_u64 v[250:251], v[250:251], 0, s[98:99]
	s_nop 0
	global_load_ushort v225, v[250:251], off
	v_lshl_add_u64 v[250:251], v[250:251], 0, s[98:99]
	s_nop 0
	global_load_ushort v226, v[250:251], off
	v_lshl_add_u64 v[250:251], v[250:251], 0, s[98:99]
	s_nop 0
	global_load_ushort v227, v[250:251], off
	v_lshl_add_u64 v[250:251], v[250:251], 0, s[98:99]
	s_nop 0
	global_load_ushort v228, v[250:251], off
	v_lshl_add_u64 v[250:251], v[250:251], 0, s[98:99]
	s_nop 0
	global_load_ushort v229, v[250:251], off
	v_lshl_add_u64 v[250:251], v[250:251], 0, s[98:99]
	s_nop 0
	global_load_ushort v230, v[250:251], off
	v_lshl_add_u64 v[250:251], v[250:251], 0, s[98:99]
	s_nop 0
	global_load_ushort v231, v[250:251], off
	v_lshl_add_u64 v[250:251], v[250:251], 0, s[98:99]
	s_nop 0
	global_load_ushort v232, v[250:251], off
	v_lshl_add_u64 v[250:251], v[250:251], 0, s[98:99]
	s_nop 0
	global_load_ushort v233, v[250:251], off
	v_lshl_add_u64 v[250:251], v[250:251], 0, s[98:99]
	s_nop 0
	global_load_ushort v234, v[250:251], off
	v_lshl_add_u64 v[250:251], v[250:251], 0, s[98:99]
	s_nop 0
	global_load_ushort v235, v[250:251], off
	v_lshl_add_u64 v[250:251], v[250:251], 0, s[98:99]
	s_nop 0
	global_load_ushort v240, v[250:251], off
	v_lshl_add_u64 v[250:251], v[250:251], 0, s[98:99]
	s_nop 0
	global_load_ushort v241, v[250:251], off
	v_lshl_add_u64 v[250:251], v[250:251], 0, s[98:99]
	s_nop 0
	global_load_ushort v242, v[250:251], off
	v_lshl_add_u64 v[250:251], v[250:251], 0, s[98:99]
	s_nop 0
	global_load_ushort v243, v[250:251], off
	v_lshl_add_u64 v[250:251], v[250:251], 0, s[98:99]
	s_nop 0
	global_load_ushort v248, v[250:251], off
	v_lshl_add_u64 v[250:251], v[250:251], 0, s[98:99]
	s_nop 0
	global_load_ushort v249, v[250:251], off
	v_lshl_add_u64 v[250:251], v[250:251], 0, s[98:99]
	v_mad_u64_u32 v[6:7], s[0:1], v2, s6, v[6:7]
	s_mov_b32 s0, 0xb209000
	s_nop 0
	v_add_co_u32_e32 v10, vcc, s0, v0
	s_mov_b32 s0, 0xb20a000
	s_nop 0
	v_addc_co_u32_e32 v11, vcc, 0, v1, vcc
	v_add_co_u32_e32 v12, vcc, s0, v0
	s_mov_b32 s0, 0xb20b000
	s_nop 0
	v_addc_co_u32_e32 v13, vcc, 0, v1, vcc
	v_add_co_u32_e32 v14, vcc, s0, v0
	s_mov_b32 s0, 0xb20c000
	s_nop 0
	v_addc_co_u32_e32 v15, vcc, 0, v1, vcc
	v_add_co_u32_e32 v16, vcc, s0, v0
	s_mov_b32 s0, 0xb20d000
	s_nop 0
	v_addc_co_u32_e32 v17, vcc, 0, v1, vcc
	v_add_co_u32_e32 v18, vcc, s0, v0
	s_mov_b32 s0, 0xb20f000
	s_nop 0
	v_addc_co_u32_e32 v19, vcc, 0, v1, vcc
	v_lshlrev_b32_e32 v160, 1, v3
	v_add_co_u32_e32 v20, vcc, s0, v0
	v_lshl_add_u64 v[2:3], v[6:7], 0, v[160:161]
	s_nop 0
	v_addc_co_u32_e32 v21, vcc, 0, v1, vcc
	s_mov_b32 s0, 0x19300000
	v_add_co_u32_e32 v22, vcc, s0, v2
	s_mov_b32 s0, 0xb210000
	s_nop 0
	v_addc_co_u32_e32 v23, vcc, 0, v3, vcc
	v_readlane_b32 s10, v255, 11
	v_readlane_b32 s11, v255, 12
	v_mov_b32_e32 v60, 0
	s_mov_b32 s14, 0
	v_mov_b32_e32 v38, 0
	v_mov_b32_e32 v39, v60
	v_mov_b32_e32 v36, 0
	v_mov_b32_e32 v37, v60
	s_waitcnt vmcnt(0)
	v_lshl_or_b32 v6, v9, 16, v8
	v_lshl_or_b32 v7, v25, 16, v24
	v_lshl_or_b32 v8, v27, 16, v26
	v_lshl_or_b32 v9, v29, 16, v28
	global_store_dwordx4 v[22:23], v[6:9], off
	s_nop 1
	v_add_co_u32_e32 v6, vcc, s0, v0
	s_mov_b32 s0, 0xb211000
	s_nop 0
	v_addc_co_u32_e32 v7, vcc, 0, v1, vcc
	v_add_co_u32_e32 v8, vcc, s0, v0
	s_mov_b32 s0, 0xb212000
	s_nop 0
	v_addc_co_u32_e32 v9, vcc, 0, v1, vcc
	global_load_ushort v5, v[10:11], off offset:1792
	global_load_ushort v26, v[12:13], off offset:2304
	global_load_ushort v27, v[14:15], off offset:2816
	global_load_ushort v28, v[16:17], off offset:3328
	global_load_ushort v29, v[18:19], off offset:3840
	global_load_ushort v30, v[20:21], off offset:256
	global_load_ushort v31, v[6:7], off offset:768
	s_nop 0
	global_load_ushort v9, v[8:9], off offset:1280
	v_add_co_u32_e32 v10, vcc, s0, v0
	s_mov_b32 s0, 0xb213000
	s_nop 0
	v_addc_co_u32_e32 v11, vcc, 0, v1, vcc
	v_add_co_u32_e32 v12, vcc, s0, v0
	s_mov_b32 s0, 0xb214000
	s_nop 0
	v_addc_co_u32_e32 v13, vcc, 0, v1, vcc
	v_add_co_u32_e32 v14, vcc, s0, v0
	s_mov_b32 s0, 0xb215000
	s_nop 0
	v_addc_co_u32_e32 v15, vcc, 0, v1, vcc
	v_add_co_u32_e32 v16, vcc, s0, v0
	s_mov_b32 s0, 0xb216000
	s_nop 0
	v_addc_co_u32_e32 v17, vcc, 0, v1, vcc
	v_add_co_u32_e32 v18, vcc, s0, v0
	s_mov_b32 s0, 0xb218000
	s_nop 0
	v_addc_co_u32_e32 v19, vcc, 0, v1, vcc
	v_add_co_u32_e32 v20, vcc, s0, v0
	s_mov_b32 s0, 0xb219000
	s_nop 0
	v_addc_co_u32_e32 v21, vcc, 0, v1, vcc
	v_add_co_u32_e32 v22, vcc, s0, v0
	s_mov_b32 s0, 0xb21a000
	s_nop 0
	v_addc_co_u32_e32 v23, vcc, 0, v1, vcc
	v_add_co_u32_e32 v24, vcc, s0, v0
	s_mov_b64 s[0:1], 0x19300000
	v_lshl_add_u64 v[2:3], v[2:3], 0, s[0:1]
	v_addc_co_u32_e32 v25, vcc, 0, v1, vcc
	s_mov_b32 s0, 0xb21b000
	s_waitcnt vmcnt(0)
	v_lshl_or_b32 v6, v26, 16, v5
	v_lshl_or_b32 v7, v28, 16, v27
	v_lshl_or_b32 v8, v30, 16, v29
	v_lshl_or_b32 v9, v9, 16, v31
	global_store_dwordx4 v[2:3], v[6:9], off offset:16
	global_load_ushort v5, v[10:11], off offset:1792
	s_nop 0
	global_load_ushort v6, v[12:13], off offset:2304
	global_load_ushort v7, v[14:15], off offset:2816
	global_load_ushort v8, v[16:17], off offset:3328
	global_load_ushort v9, v[18:19], off offset:3840
	global_load_ushort v26, v[20:21], off offset:256
	global_load_ushort v27, v[22:23], off offset:768
	global_load_ushort v28, v[24:25], off offset:1280
	v_add_co_u32_e32 v10, vcc, s0, v0
	s_mov_b32 s0, 0xb21c000
	s_nop 0
	v_addc_co_u32_e32 v11, vcc, 0, v1, vcc
	v_add_co_u32_e32 v12, vcc, s0, v0
	s_mov_b32 s0, 0xb21d000
	s_nop 0
	v_addc_co_u32_e32 v13, vcc, 0, v1, vcc
	v_add_co_u32_e32 v14, vcc, s0, v0
	s_mov_b32 s0, 0xb21e000
	s_nop 0
	v_addc_co_u32_e32 v15, vcc, 0, v1, vcc
	v_add_co_u32_e32 v16, vcc, s0, v0
	s_mov_b32 s0, 0xb21f000
	s_nop 0
	v_addc_co_u32_e32 v17, vcc, 0, v1, vcc
	v_add_co_u32_e32 v18, vcc, s0, v0
	s_mov_b32 s0, 0xb221000
	s_nop 0
	v_addc_co_u32_e32 v19, vcc, 0, v1, vcc
	v_add_co_u32_e32 v20, vcc, s0, v0
	s_mov_b32 s0, 0xb222000
	s_nop 0
	v_addc_co_u32_e32 v21, vcc, 0, v1, vcc
	v_add_co_u32_e32 v22, vcc, s0, v0
	s_mov_b32 s0, 0xb223000
	s_nop 0
	v_addc_co_u32_e32 v23, vcc, 0, v1, vcc
	v_add_co_u32_e32 v24, vcc, s0, v0
	s_mov_b32 s0, 0xb224000
	s_nop 0
	v_addc_co_u32_e32 v25, vcc, 0, v1, vcc
	s_waitcnt vmcnt(0)
	v_lshl_or_b32 v6, v6, 16, v5
	v_lshl_or_b32 v7, v8, 16, v7
	v_lshl_or_b32 v8, v26, 16, v9
	v_lshl_or_b32 v9, v28, 16, v27
	global_store_dwordx4 v[2:3], v[6:9], off offset:32
	global_load_ushort v5, v[10:11], off offset:1792
	s_nop 0
	global_load_ushort v6, v[12:13], off offset:2304
	global_load_ushort v7, v[14:15], off offset:2816
	global_load_ushort v8, v[16:17], off offset:3328
	global_load_ushort v9, v[18:19], off offset:3840
	global_load_ushort v26, v[20:21], off offset:256
	global_load_ushort v27, v[22:23], off offset:768
	global_load_ushort v28, v[24:25], off offset:1280
	v_add_co_u32_e32 v10, vcc, s0, v0
	s_mov_b32 s0, 0xb225000
	s_nop 0
	v_addc_co_u32_e32 v11, vcc, 0, v1, vcc
	v_add_co_u32_e32 v12, vcc, s0, v0
	s_mov_b32 s0, 0xb226000
	s_nop 0
	v_addc_co_u32_e32 v13, vcc, 0, v1, vcc
	v_add_co_u32_e32 v14, vcc, s0, v0
	s_mov_b32 s0, 0xb227000
	s_nop 0
	v_addc_co_u32_e32 v15, vcc, 0, v1, vcc
	v_add_co_u32_e32 v16, vcc, s0, v0
	s_mov_b32 s0, 0xb228000
	s_nop 0
	v_addc_co_u32_e32 v17, vcc, 0, v1, vcc
	v_add_co_u32_e32 v18, vcc, s0, v0
	s_mov_b32 s0, 0xb22a000
	s_nop 0
	v_addc_co_u32_e32 v19, vcc, 0, v1, vcc
	v_add_co_u32_e32 v20, vcc, s0, v0
	s_mov_b32 s0, 0xb22b000
	s_nop 0
	v_addc_co_u32_e32 v21, vcc, 0, v1, vcc
	v_add_co_u32_e32 v22, vcc, s0, v0
	s_mov_b32 s0, 0xb22c000
	s_nop 0
	v_addc_co_u32_e32 v23, vcc, 0, v1, vcc
	v_add_co_u32_e32 v24, vcc, s0, v0
	s_mov_b32 s0, 0xb22d000
	s_nop 0
	v_addc_co_u32_e32 v25, vcc, 0, v1, vcc
	s_waitcnt vmcnt(0)
	v_lshl_or_b32 v6, v6, 16, v5
	v_lshl_or_b32 v7, v8, 16, v7
	v_lshl_or_b32 v8, v26, 16, v9
	v_lshl_or_b32 v9, v28, 16, v27
	global_store_dwordx4 v[2:3], v[6:9], off offset:48
	global_load_ushort v5, v[10:11], off offset:1792
	s_nop 0
	global_load_ushort v6, v[12:13], off offset:2304
	global_load_ushort v7, v[14:15], off offset:2816
	global_load_ushort v8, v[16:17], off offset:3328
	global_load_ushort v9, v[18:19], off offset:3840
	global_load_ushort v26, v[20:21], off offset:256
	global_load_ushort v27, v[22:23], off offset:768
	global_load_ushort v28, v[24:25], off offset:1280
	v_add_co_u32_e32 v10, vcc, s0, v0
	s_mov_b32 s0, 0xb22e000
	s_nop 0
	v_addc_co_u32_e32 v11, vcc, 0, v1, vcc
	v_add_co_u32_e32 v12, vcc, s0, v0
	s_mov_b32 s0, 0xb22f000
	s_nop 0
	v_addc_co_u32_e32 v13, vcc, 0, v1, vcc
	v_add_co_u32_e32 v14, vcc, s0, v0
	s_mov_b32 s0, 0xb230000
	s_nop 0
	v_addc_co_u32_e32 v15, vcc, 0, v1, vcc
	v_add_co_u32_e32 v16, vcc, s0, v0
	s_mov_b32 s0, 0xb231000
	s_nop 0
	v_addc_co_u32_e32 v17, vcc, 0, v1, vcc
	v_add_co_u32_e32 v18, vcc, s0, v0
	s_mov_b32 s0, 0xb233000
	s_nop 0
	v_addc_co_u32_e32 v19, vcc, 0, v1, vcc
	v_add_co_u32_e32 v20, vcc, s0, v0
	s_mov_b32 s0, 0xb234000
	s_nop 0
	v_addc_co_u32_e32 v21, vcc, 0, v1, vcc
	v_add_co_u32_e32 v22, vcc, s0, v0
	s_mov_b32 s0, 0xb235000
	s_nop 0
	v_addc_co_u32_e32 v23, vcc, 0, v1, vcc
	v_add_co_u32_e32 v24, vcc, s0, v0
	s_mov_b32 s0, 0xb236000
	s_nop 0
	v_addc_co_u32_e32 v25, vcc, 0, v1, vcc
	s_waitcnt vmcnt(0)
	v_lshl_or_b32 v6, v6, 16, v5
	v_lshl_or_b32 v7, v8, 16, v7
	v_lshl_or_b32 v8, v26, 16, v9
	v_lshl_or_b32 v9, v28, 16, v27
	global_store_dwordx4 v[2:3], v[6:9], off offset:64
	global_load_ushort v5, v[10:11], off offset:1792
	s_nop 0
	global_load_ushort v6, v[12:13], off offset:2304
	global_load_ushort v7, v[14:15], off offset:2816
	global_load_ushort v8, v[16:17], off offset:3328
	global_load_ushort v9, v[18:19], off offset:3840
	global_load_ushort v26, v[20:21], off offset:256
	global_load_ushort v27, v[22:23], off offset:768
	global_load_ushort v28, v[24:25], off offset:1280
	v_add_co_u32_e32 v10, vcc, s0, v0
	s_mov_b32 s0, 0xb237000
	s_nop 0
	v_addc_co_u32_e32 v11, vcc, 0, v1, vcc
	v_add_co_u32_e32 v12, vcc, s0, v0
	s_mov_b32 s0, 0xb238000
	s_nop 0
	v_addc_co_u32_e32 v13, vcc, 0, v1, vcc
	v_add_co_u32_e32 v14, vcc, s0, v0
	s_mov_b32 s0, 0xb239000
	s_nop 0
	v_addc_co_u32_e32 v15, vcc, 0, v1, vcc
	v_add_co_u32_e32 v16, vcc, s0, v0
	s_mov_b32 s0, 0xb23a000
	s_nop 0
	v_addc_co_u32_e32 v17, vcc, 0, v1, vcc
	v_add_co_u32_e32 v18, vcc, s0, v0
	s_mov_b32 s0, 0xb23c000
	s_nop 0
	v_addc_co_u32_e32 v19, vcc, 0, v1, vcc
	v_add_co_u32_e32 v20, vcc, s0, v0
	s_mov_b32 s0, 0xb23d000
	s_nop 0
	v_addc_co_u32_e32 v21, vcc, 0, v1, vcc
	v_add_co_u32_e32 v22, vcc, s0, v0
	s_mov_b32 s0, 0xb23e000
	s_nop 0
	v_addc_co_u32_e32 v23, vcc, 0, v1, vcc
	v_add_co_u32_e32 v24, vcc, s0, v0
	s_mov_b32 s0, 0xb23f000
	s_nop 0
	v_addc_co_u32_e32 v25, vcc, 0, v1, vcc
	s_waitcnt vmcnt(0)
	v_lshl_or_b32 v6, v6, 16, v5
	v_lshl_or_b32 v7, v8, 16, v7
	v_lshl_or_b32 v8, v26, 16, v9
	v_lshl_or_b32 v9, v28, 16, v27
	global_store_dwordx4 v[2:3], v[6:9], off offset:80
	global_load_ushort v5, v[10:11], off offset:1792
	s_nop 0
	global_load_ushort v6, v[12:13], off offset:2304
	global_load_ushort v7, v[14:15], off offset:2816
	global_load_ushort v8, v[16:17], off offset:3328
	global_load_ushort v9, v[18:19], off offset:3840
	global_load_ushort v26, v[20:21], off offset:256
	global_load_ushort v27, v[22:23], off offset:768
	s_nop 0
	global_load_ushort v24, v[24:25], off offset:1280
	v_add_co_u32_e32 v10, vcc, s0, v0
	s_mov_b32 s0, 0xb240000
	s_nop 0
	v_addc_co_u32_e32 v11, vcc, 0, v1, vcc
	v_add_co_u32_e32 v12, vcc, s0, v0
	s_mov_b32 s0, 0xb241000
	s_nop 0
	v_addc_co_u32_e32 v13, vcc, 0, v1, vcc
	v_add_co_u32_e32 v14, vcc, s0, v0
	s_mov_b32 s0, 0xb242000
	s_nop 0
	v_addc_co_u32_e32 v15, vcc, 0, v1, vcc
	v_add_co_u32_e32 v16, vcc, s0, v0
	s_mov_b32 s0, 0xb243000
	s_nop 0
	v_addc_co_u32_e32 v17, vcc, 0, v1, vcc
	v_add_co_u32_e32 v18, vcc, s0, v0
	s_mov_b32 s0, 0xb245000
	s_nop 0
	v_addc_co_u32_e32 v19, vcc, 0, v1, vcc
	v_add_co_u32_e32 v20, vcc, s0, v0
	s_mov_b32 s0, 0xb246000
	s_nop 0
	v_addc_co_u32_e32 v21, vcc, 0, v1, vcc
	v_add_co_u32_e32 v22, vcc, s0, v0
	s_mov_b32 s0, 0xb247000
	s_nop 0
	v_addc_co_u32_e32 v23, vcc, 0, v1, vcc
	v_add_co_u32_e32 v0, vcc, s0, v0
	v_readlane_b32 s0, v255, 7
	s_nop 0
	v_addc_co_u32_e32 v1, vcc, 0, v1, vcc
	v_readlane_b32 s1, v255, 8
	s_lshl_b64 s[0:1], s[0:1], 2
	s_add_u32 s0, s8, s0
	s_addc_u32 s1, s9, s1
	s_waitcnt vmcnt(0)
	v_lshl_or_b32 v6, v6, 16, v5
	v_lshl_or_b32 v7, v8, 16, v7
	v_lshl_or_b32 v8, v26, 16, v9
	v_lshl_or_b32 v9, v24, 16, v27
	global_store_dwordx4 v[2:3], v[6:9], off offset:96
	global_load_ushort v5, v[10:11], off offset:1792
	s_nop 0
	global_load_ushort v6, v[12:13], off offset:2304
	global_load_ushort v7, v[14:15], off offset:2816
	global_load_ushort v10, v[16:17], off offset:3328
	global_load_ushort v11, v[18:19], off offset:3840
	s_nop 0
	global_load_ushort v12, v[20:21], off offset:256
	global_load_ushort v13, v[22:23], off offset:768
	global_load_ushort v14, v[0:1], off offset:1280
	v_mov_b32_e32 v0, 0x300
	v_lshl_add_u32 v54, v4, 3, v0
	v_mov_b32_e32 v15, v236
	v_mov_b64_e32 v[0:1], s[10:11]
	v_mad_u64_u32 v[8:9], s[4:5], v54, s6, v[0:1]
	s_waitcnt vmcnt(0)
	v_lshl_or_b32 v4, v6, 16, v5
	v_lshl_or_b32 v5, v10, 16, v7
	v_lshl_or_b32 v6, v12, 16, v11
	v_lshl_or_b32 v7, v14, 16, v13
	global_store_dwordx4 v[2:3], v[4:7], off offset:112
	s_nop 0
	v_and_b32_e32 v14, 15, v15
	v_bfe_u32 v17, v15, 4, 2
	v_lshlrev_b32_e32 v19, 2, v14
	v_lshlrev_b32_e32 v2, 6, v17
	v_or_b32_e32 v21, 8, v17
	v_lshlrev_b32_e32 v160, 4, v14
	v_or_b32_e32 v23, 0x100, v19
	v_min_u32_e32 v3, 9, v21
	v_or_b32_e32 v20, v2, v19
	v_lshl_add_u64 v[0:1], s[0:1], 0, v[160:161]
	v_or_b32_e32 v16, v2, v23
	v_lshlrev_b32_e32 v24, 6, v3
	s_mov_b64 s[0:1], 0x2000
	v_lshlrev_b32_e32 v160, 1, v20
	v_lshl_add_u64 v[4:5], v[0:1], 0, s[0:1]
	v_add_co_u32_e32 v0, vcc, s20, v0
	v_lshl_add_u64 v[10:11], v[8:9], 0, v[160:161]
	v_lshlrev_b32_e32 v160, 1, v16
	v_or_b32_e32 v22, v24, v19
	v_addc_co_u32_e32 v1, vcc, 0, v1, vcc
	v_lshl_add_u64 v[12:13], v[8:9], 0, v[160:161]
	v_lshlrev_b32_e32 v160, 1, v22
	global_load_dwordx4 v[0:3], v[0:1], off
	s_nop 0
	global_load_dwordx4 v[4:7], v[4:5], off offset:1024
	v_lshl_add_u64 v[8:9], v[8:9], 0, v[160:161]
	global_load_dwordx2 v[42:43], v[10:11], off offset:512
	global_load_dwordx2 v[40:41], v[12:13], off offset:512
	global_load_dwordx2 v[34:35], v[8:9], off offset:512
	v_and_b32_e32 v8, 63, v15
	v_and_b32_e32 v9, 4, v15
	v_lshlrev_b32_e32 v160, 3, v8
	v_cmp_eq_u32_e64 s[36:37], 0, v9
	v_cmp_gt_u32_e64 s[38:39], 8, v14
	v_and_b32_e32 v14, 12, v19
	v_lshl_add_u64 v[8:9], s[8:9], 0, v[160:161]
	s_mov_b64 s[0:1], 0x16f00000
	v_lshl_add_u64 v[12:13], v[8:9], 0, s[0:1]
	v_cvt_f32_ubyte0_e32 v8, v14
	v_mul_f32_e32 v8, 0xbf549a78, v8
	v_exp_f32_e32 v56, v8
	v_or_b32_e32 v8, 1, v14
	v_cvt_f32_ubyte0_e32 v8, v8
	v_mul_f32_e32 v8, 0xbf549a78, v8
	v_exp_f32_e32 v57, v8
	v_or_b32_e32 v8, 2, v14
	v_cvt_f32_ubyte0_e32 v8, v8
	v_mul_f32_e32 v8, 0xbf549a78, v8
	v_exp_f32_e32 v58, v8
	v_or_b32_e32 v8, 3, v14
	v_cvt_f32_ubyte0_e32 v8, v8
	v_mul_f32_e32 v8, 0xbf549a78, v8
	v_exp_f32_e32 v59, v8
	v_mad_i64_i32 v[8:9], s[0:1], v54, s6, 0
	v_add_u32_e32 v18, 0x100, v16
	v_or_b32_e32 v24, v24, v23
	v_or_b32_e32 v8, v8, v160
	v_cmp_gt_u32_e32 vcc, 10, v21
	v_lshlrev_b32_e64 v55, v17, 1
	v_lshl_add_u64 v[10:11], s[10:11], 0, v[160:161]
	v_lshl_add_u64 v[14:15], s[10:11], 0, v[8:9]
	v_lshlrev_b32_e32 v8, 1, v16
	v_lshlrev_b32_e32 v16, 1, v18
	v_lshlrev_b32_e32 v18, 1, v24
	v_lshlrev_b32_e32 v20, 1, v20
	v_lshlrev_b32_e32 v22, 1, v22
	v_mov_b32_e32 v21, 0
	s_waitcnt vmcnt(0)
	s_branch .LBB0_508
.LBB0_507:
	s_or_b64 exec, exec, s[0:1]
	v_sub_u32_e32 v9, v17, v60
	v_cvt_f32_i32_e32 v9, v9
	s_waitcnt vmcnt(2)
	v_lshlrev_b32_e32 v200, 16, v196
	v_and_b32_e32 v201, 0xffff0000, v196
	v_lshlrev_b32_e32 v202, 16, v198
	v_and_b32_e32 v203, 0xffff0000, v198
	v_pk_add_f32 v[200:201], v[200:201], v[202:203] neg_lo:[0,1] neg_hi:[0,1]
	v_lshlrev_b32_e32 v198, 16, v199
	v_pk_add_f32 v[36:37], v[36:37], v[200:201]
	v_lshlrev_b32_e32 v200, 16, v197
	v_and_b32_e32 v201, 0xffff0000, v197
	v_and_b32_e32 v199, 0xffff0000, v199
	v_pk_add_f32 v[200:201], v[200:201], v[198:199] neg_lo:[0,1] neg_hi:[0,1]
	s_nop 0
	v_pk_add_f32 v[38:39], v[38:39], v[200:201]
	v_bfe_u32 v222, v236, 4, 2
	v_lshlrev_b32_e64 v222, v222, 1
	v_add_u32_e32 v222, -1, v222
	v_mul_u32_u24_e32 v208, 0x1200, v222
	v_mov_b32_e32 v209, 0
	v_lshl_add_u64 v[212:213], v[206:207], 0, v[208:209]
	s_nop 1
	global_load_dwordx2 v[216:217], v[206:207], off
	global_load_dwordx2 v[218:219], v[212:213], off
	v_lshlrev_b32_e32 v34, 16, v32
	v_and_b32_e32 v35, 0xffff0000, v32
	s_add_i32 s14, s14, 1
	v_rcp_iflag_f32_e32 v30, v9
	v_lshl_add_u64 v[14:15], v[14:15], 0, s[34:35]
	s_cmp_eq_u32 s14, 8
	v_mov_b32_e32 v21, v17
	v_pk_fma_f32 v[34:35], v[30:31], v[36:37], v[34:35] op_sel_hi:[0,1,1] neg_lo:[0,0,1] neg_hi:[0,0,1]
	v_cvt_pk_bf16_f32 v32, v34, v35
	v_lshlrev_b32_e32 v34, 16, v33
	v_and_b32_e32 v35, 0xffff0000, v33
	v_pk_fma_f32 v[30:31], v[30:31], v[38:39], v[34:35] op_sel_hi:[0,1,1] neg_lo:[0,0,1] neg_hi:[0,0,1]
	v_cvt_pk_bf16_f32 v33, v30, v31
	v_lshlrev_b64 v[30:31], 11, v[160:161]
	v_lshl_add_u64 v[30:31], v[12:13], 0, v[30:31]
	v_mov_b32_e32 v42, v24
	v_mov_b32_e32 v43, v25
	v_mov_b32_e32 v40, v26
	v_mov_b32_e32 v41, v27
	v_mov_b32_e32 v34, v28
	v_mov_b32_e32 v35, v29
	global_store_dwordx2 v[30:31], v[32:33], off
	s_cbranch_scc1 .LBB0_530

.LBB0_510:
	s_movk_i32 s0, 0x3fff
	v_cmp_lt_u32_e64 s[40:41], s0, v160
	v_mov_b32_e32 v9, 0x7ff
	s_movk_i32 s0, 0x1200
	v_cndmask_b32_e64 v9, v9, v238, s[40:41]
	v_and_b32_e32 v9, v9, v160
	v_sub_u32_e32 v17, v160, v9
	v_mad_i64_i32 v[44:45], s[0:1], v17, s0, v[10:11]
	v_mul_u32_u24_e32 v17, 0x900, v9
	v_lshlrev_b32_e32 v32, 1, v17
	v_mov_b32_e32 v33, v161
	v_lshl_add_u64 v[32:33], v[44:45], 0, v[32:33]
	s_movk_i32 s98, 0x2400
	s_mov_b32 s99, 0
	v_lshl_add_u64 v[206:207], v[32:33], 0, s[98:99]
	global_load_dwordx2 v[32:33], v[32:33], off
	v_mov_b32_e32 v17, 0x800
	s_cmp_lg_u32 s14, 0
	v_cndmask_b32_e64 v17, v17, v245, s[40:41]
	v_add_u32_e32 v23, v9, v55
	s_cselect_b64 s[4:5], -1, 0
	v_cmp_ne_u32_e64 s[0:1], 0, v9
	v_sub_u32_e32 v19, v9, v55
	v_min_u32_e32 v17, v23, v17
	s_and_b64 s[0:1], s[4:5], s[0:1]
	v_mov_b32_e32 v196, 0
	v_mov_b32_e32 v197, 0
	v_mov_b32_e32 v198, 0
	v_mov_b32_e32 v199, 0
	s_and_saveexec_b64 s[4:5], s[0:1]
	s_xor_b64 s[4:5], exec, s[4:5]
	s_cbranch_execz .LBB0_516
	v_cmp_gt_u32_e64 s[0:1], v17, v21
	v_mov_b32_e32 v198, 0
	v_mov_b32_e32 v196, 0
	v_mov_b32_e32 v197, 0
	s_and_saveexec_b64 s[6:7], s[0:1]
	s_cbranch_execz .LBB0_513
	v_add_u32_e32 v21, -1, v17
	s_movk_i32 s0, 0x1200
	v_mad_u64_u32 v[48:49], s[0:1], v21, s0, v[44:45]
	global_load_dwordx2 v[196:197], v[48:49], off

.LBB0_531:
	s_andn2_saveexec_b64 s[2:3], s[42:43]
	s_cbranch_execz .LBB0_556
	v_readlane_b32 s0, v255, 7
	v_mov_b32_e32 v9, v236
	v_readlane_b32 s1, v255, 8
	s_lshl_b64 s[0:1], s[0:1], 2
	v_bfe_u32 v19, v9, 4, 2
	v_readlane_b32 s4, v254, 28
	v_and_b32_e32 v17, 15, v9
	v_or_b32_e32 v23, 8, v19
	v_readlane_b32 s5, v254, 29
	s_add_u32 s0, s4, s0
	v_min_u32_e32 v0, 9, v23
	s_addc_u32 s1, s5, s1
	v_lshlrev_b32_e32 v160, 4, v17
	v_readlane_b32 s6, v255, 11
	v_lshlrev_b32_e32 v21, 2, v17
	v_lshlrev_b32_e32 v12, 6, v19
	v_lshlrev_b32_e32 v24, 6, v0
	v_lshl_add_u64 v[0:1], s[0:1], 0, v[160:161]
	s_mov_b64 s[0:1], 0x2000
	v_readlane_b32 s7, v255, 12
	v_lshl_add_u32 v56, v81, 1, v81
	v_or_b32_e32 v18, 0x100, v21
	v_lshl_add_u64 v[4:5], v[0:1], 0, s[0:1]
	v_mov_b64_e32 v[10:11], s[6:7]
	s_movk_i32 s0, 0x1200
	v_or_b32_e32 v20, v12, v21
	v_or_b32_e32 v8, v12, v18
	v_mad_i64_i32 v[10:11], s[0:1], v56, s0, v[10:11]
	v_lshlrev_b32_e32 v160, 1, v20
	v_add_co_u32_e32 v0, vcc, s20, v0
	v_lshl_add_u64 v[12:13], v[10:11], 0, v[160:161]
	v_lshlrev_b32_e32 v160, 1, v8
	v_or_b32_e32 v22, v24, v21
	v_addc_co_u32_e32 v1, vcc, 0, v1, vcc
	v_lshl_add_u64 v[14:15], v[10:11], 0, v[160:161]
	v_lshlrev_b32_e32 v160, 1, v22
	global_load_dwordx4 v[0:3], v[0:1], off
	s_nop 0
	global_load_dwordx4 v[4:7], v[4:5], off offset:1024
	v_lshl_add_u64 v[10:11], v[10:11], 0, v[160:161]
	global_load_dwordx2 v[44:45], v[12:13], off offset:512
	global_load_dwordx2 v[42:43], v[14:15], off offset:512
	global_load_dwordx2 v[36:37], v[10:11], off offset:512
	v_and_b32_e32 v10, 63, v9
	v_and_b32_e32 v9, 4, v9
	v_cmp_eq_u32_e64 s[36:37], 0, v9
	v_and_b32_e32 v9, 12, v21
	v_cmp_gt_u32_e64 s[38:39], 8, v17
	v_cvt_f32_ubyte0_e32 v17, v9
	v_mul_f32_e32 v17, 0xbf549a78, v17
	v_exp_f32_e32 v58, v17
	v_or_b32_e32 v17, 1, v9
	v_cvt_f32_ubyte0_e32 v17, v17
	v_mul_f32_e32 v17, 0xbf549a78, v17
	v_exp_f32_e32 v59, v17
	v_or_b32_e32 v17, 2, v9
	v_or_b32_e32 v9, 3, v9
	v_cvt_f32_ubyte0_e32 v17, v17
	v_cvt_f32_ubyte0_e32 v9, v9
	v_mul_f32_e32 v17, 0xbf549a78, v17
	v_mul_f32_e32 v9, 0xbf549a78, v9
	v_exp_f32_e32 v60, v17
	v_exp_f32_e32 v61, v9
	v_lshlrev_b32_e32 v160, 3, v10
	v_add_u32_e32 v16, 0x100, v8
	v_or_b32_e32 v18, v24, v18
	v_mov_b32_e32 v63, 0
	v_lshl_add_u64 v[12:13], s[4:5], 0, v[160:161]
	s_mov_b64 s[0:1], 0x16f00000
	v_cmp_gt_u32_e32 vcc, 10, v23
	v_lshlrev_b32_e64 v57, v19, 1
	v_lshl_add_u64 v[10:11], s[6:7], 0, v[160:161]
	v_lshl_add_u64 v[14:15], v[12:13], 0, s[0:1]
	s_mov_b32 s14, 0
	v_lshlrev_b32_e32 v8, 1, v8
	v_lshlrev_b32_e32 v16, 1, v16
	v_lshlrev_b32_e32 v18, 1, v18
	v_lshlrev_b32_e32 v20, 1, v20
	v_lshlrev_b32_e32 v22, 1, v22
	v_mov_b32_e32 v62, v56
	v_mov_b32_e32 v21, 0
	v_mov_b32_e32 v38, 0
	v_mov_b32_e32 v39, v63
	v_mov_b32_e32 v40, 0
	v_mov_b32_e32 v41, v63
	s_waitcnt vmcnt(0)
	s_branch .LBB0_534
.LBB0_533:
	s_or_b64 exec, exec, s[0:1]
	v_sub_u32_e32 v9, v17, v63
	v_cvt_f32_i32_e32 v9, v9
	s_waitcnt vmcnt(2)
	v_lshlrev_b32_e32 v200, 16, v196
	v_and_b32_e32 v201, 0xffff0000, v196
	v_lshlrev_b32_e32 v202, 16, v198
	v_and_b32_e32 v203, 0xffff0000, v198
	v_pk_add_f32 v[200:201], v[200:201], v[202:203] neg_lo:[0,1] neg_hi:[0,1]
	v_lshlrev_b32_e32 v198, 16, v199
	v_pk_add_f32 v[40:41], v[40:41], v[200:201]
	v_lshlrev_b32_e32 v200, 16, v197
	v_and_b32_e32 v201, 0xffff0000, v197
	v_and_b32_e32 v199, 0xffff0000, v199
	v_pk_add_f32 v[200:201], v[200:201], v[198:199] neg_lo:[0,1] neg_hi:[0,1]
	s_nop 0
	v_pk_add_f32 v[38:39], v[38:39], v[200:201]
	v_bfe_u32 v222, v236, 4, 2
	v_lshlrev_b32_e64 v222, v222, 1
	v_add_u32_e32 v222, -1, v222
	v_mul_u32_u24_e32 v208, 0x1200, v222
	v_mov_b32_e32 v209, 0
	v_lshl_add_u64 v[212:213], v[206:207], 0, v[208:209]
	s_nop 1
	global_load_dwordx2 v[216:217], v[206:207], off
	global_load_dwordx2 v[218:219], v[212:213], off
	v_lshlrev_b32_e32 v36, 16, v34
	v_and_b32_e32 v37, 0xffff0000, v34
	s_add_i32 s14, s14, 1
	v_rcp_iflag_f32_e32 v32, v9
	v_lshlrev_b64 v[24:25], 11, v[24:25]
	v_lshl_add_u64 v[24:25], v[14:15], 0, v[24:25]
	v_add_u32_e32 v62, 1, v62
	v_pk_fma_f32 v[36:37], v[32:33], v[40:41], v[36:37] op_sel_hi:[0,1,1] neg_lo:[0,0,1] neg_hi:[0,0,1]
	v_cvt_pk_bf16_f32 v34, v36, v37
	v_lshlrev_b32_e32 v36, 16, v35
	v_and_b32_e32 v37, 0xffff0000, v35
	v_pk_fma_f32 v[32:33], v[32:33], v[38:39], v[36:37] op_sel_hi:[0,1,1] neg_lo:[0,0,1] neg_hi:[0,0,1]
	v_cvt_pk_bf16_f32 v35, v32, v33
	s_cmp_eq_u32 s14, 3
	v_mov_b32_e32 v21, v17
	v_mov_b32_e32 v44, v26
	v_mov_b32_e32 v45, v27
	v_mov_b32_e32 v42, v28
	v_mov_b32_e32 v43, v29
	v_mov_b32_e32 v36, v30
	v_mov_b32_e32 v37, v31
	global_store_dwordx2 v[24:25], v[34:35], off
	s_cbranch_scc1 .LBB0_556
.LBB0_534:
	v_readlane_b32 s0, v255, 11
	v_readlane_b32 s1, v255, 12
	v_add_u32_e32 v24, s14, v56
	s_cmp_gt_u32 s14, 1
	v_mov_b64_e32 v[26:27], s[0:1]
	s_movk_i32 s0, 0x1200
	v_mad_i64_i32 v[32:33], s[0:1], v24, s0, v[26:27]
	v_mov_b32_e32 v26, v44
	v_mov_b32_e32 v27, v45
	v_mov_b32_e32 v28, v42
	v_mov_b32_e32 v29, v43
	v_mov_b32_e32 v30, v36
	v_mov_b32_e32 v31, v37
	s_cbranch_scc1 .LBB0_536
	v_lshl_add_u64 v[26:27], v[32:33], 0, s[34:35]
	v_mov_b32_e32 v9, v161
	v_mov_b32_e32 v17, v161
	v_lshl_add_u64 v[28:29], v[26:27], 0, v[8:9]
	v_lshl_add_u64 v[30:31], v[26:27], 0, v[16:17]
	v_mov_b32_e32 v19, v161
	v_lshl_add_u64 v[34:35], v[26:27], 0, v[18:19]
	global_load_dwordx2 v[26:27], v[28:29], off
	s_nop 0
	global_load_dwordx2 v[28:29], v[30:31], off
	s_nop 0
	global_load_dwordx2 v[30:31], v[34:35], off
.LBB0_536:
	s_movk_i32 s0, 0x3fff
	v_cmp_lt_i32_e64 s[40:41], s0, v24
	v_mov_b32_e32 v9, 0x7ff
	s_movk_i32 s0, 0x1200
	v_cndmask_b32_e64 v9, v9, v238, s[40:41]
	v_and_b32_e32 v9, v9, v24
	v_sub_u32_e32 v17, v24, v9
	v_mad_i64_i32 v[46:47], s[0:1], v17, s0, v[10:11]
	v_mul_u32_u24_e32 v17, 0x900, v9
	v_lshlrev_b32_e32 v160, 1, v17
	v_lshl_add_u64 v[34:35], v[46:47], 0, v[160:161]
	s_movk_i32 s98, 0x2400
	s_mov_b32 s99, 0
	v_lshl_add_u64 v[206:207], v[34:35], 0, s[98:99]
	global_load_dwordx2 v[34:35], v[34:35], off
	v_mov_b32_e32 v17, 0x800
	s_cmp_lg_u32 s14, 0
	v_cndmask_b32_e64 v17, v17, v245, s[40:41]
	v_add_u32_e32 v23, v9, v57
	s_cselect_b64 s[4:5], -1, 0
	v_cmp_ne_u32_e64 s[0:1], 0, v9
	v_ashrrev_i32_e32 v25, 31, v24
	v_sub_u32_e32 v19, v9, v57
	v_min_u32_e32 v17, v23, v17
	s_and_b64 s[0:1], s[4:5], s[0:1]
	v_mov_b32_e32 v196, 0
	v_mov_b32_e32 v197, 0
	v_mov_b32_e32 v198, 0
	v_mov_b32_e32 v199, 0
	s_and_saveexec_b64 s[4:5], s[0:1]
	s_xor_b64 s[4:5], exec, s[4:5]
	s_cbranch_execz .LBB0_542
	v_cmp_gt_u32_e64 s[0:1], v17, v21
	v_mov_b32_e32 v198, 0
	v_mov_b32_e32 v196, 0
	v_mov_b32_e32 v197, 0
	s_and_saveexec_b64 s[6:7], s[0:1]
	s_cbranch_execz .LBB0_539
	v_add_u32_e32 v21, -1, v17
	s_movk_i32 s0, 0x1200
	v_mad_u64_u32 v[50:51], s[0:1], v21, s0, v[46:47]
	global_load_dwordx2 v[196:197], v[50:51], off
